# FFN-in epilogue: dead v_mov that pre-set the old value of full-mask row_ror DPP moves removed (128 per tile)
# speedup vs baseline: 1.0027x; 1.0027x over previous
;     __device__ __forceinline__ void operator()(const f32x4 (&acc)[2][2][4][2], const pg8::Unit& u, int wr, int wc, int fr, int fq) const {
;     ...
;             const int c0 = u.pn * 128 + wc * 32 + 8 * fq;
;             f32x4 w0[2], w1[2], w2[2], bb[2];
; #pragma unroll
;             for (int n = 0; n < 2; ++n) { w0[n] = bf4(*(const LAS u32x2*)(cwl + c0 + 4 * n)); w1[n] = bf4(*(const LAS u32x2*)(cwl + DFF + c0 + 4 * n)); w2[n] = bf4(*(const LAS u32x2*)(cwl + 2 * DFF + c0 + 4 * n)); bb[n] = bf4(*(const LAS u32x2*)(cwl + 3 * DFF + c0 + 4 * n)); }
; #pragma unroll
;             for (int ai = 0; ai < 2; ++ai) {
;                 f32x4 p1[2] = {(f32x4){0.f, 0.f, 0.f, 0.f}, (f32x4){0.f, 0.f, 0.f, 0.f}}, p2[2] = {(f32x4){0.f, 0.f, 0.f, 0.f}, (f32x4){0.f, 0.f, 0.f, 0.f}};
; #pragma unroll
;                 for (int m = 0; m < 4; ++m) {
;                     const int row = row0 + ai * 128 + m * 16;
;                     float hv[8];
; #pragma unroll
;                     for (int n = 0; n < 2; ++n) {
;                         const f32x4 g = acc[ai][0][m][n], up = acc[ai][1][m][n];
;                         f32x4 c1, c2;
; #pragma unroll
;                         for (int j = 0; j < 4; ++j) {
;                             c1[j] = __int_as_float(__builtin_amdgcn_update_dpp(0, __float_as_int(g[j]), 0x121, 0xF, 0xF, false));
;                             c2[j] = __int_as_float(__builtin_amdgcn_update_dpp(0, __float_as_int(g[j]), 0x122, 0xF, 0xF, false)); }
;                         f32x4 g1v, g2v;
; #pragma unroll
;                         for (int j = 0; j < 4; ++j) { g1v[j] = fr >= 1 ? c1[j] : p1[n][j]; g2v[j] = fr >= 2 ? c2[j] : p2[n][j]; }
; #pragma unroll
;                         for (int hh = 0; hh < 2; ++hh) {
;                             const f32x2 gg = (f32x2){g[2 * hh], g[2 * hh + 1]}, a1 = (f32x2){g1v[2 * hh], g1v[2 * hh + 1]}, a2 = (f32x2){g2v[2 * hh], g2v[2 * hh + 1]};
;                             const f32x2 t0 = (f32x2){w0[n][2 * hh], w0[n][2 * hh + 1]}, t1 = (f32x2){w1[n][2 * hh], w1[n][2 * hh + 1]}, t2 = (f32x2){w2[n][2 * hh], w2[n][2 * hh + 1]};
;                             const f32x2 y = t0 * a2 + (t1 * a1 + (t2 * gg + (f32x2){bb[n][2 * hh], bb[n][2 * hh + 1]}));
;                             const f32x2 t = y * (-1.4426950408889634f);
;                             f32x2 d = (f32x2){__builtin_amdgcn_exp2f(t.x), __builtin_amdgcn_exp2f(t.y)} + 1.0f;
.LBB0_2826:
	v_lshl_or_b32 v146, s16, 7, v139
	v_lshl_add_u32 v147, v146, 1, 0
	v_add_u32_e32 v148, 0x20000, v147
	v_add_u32_e32 v152, 0x21600, v147
	v_add_u32_e32 v156, 0x22c00, v147
	v_add_u32_e32 v147, 0x24200, v147
	ds_read_b128 v[148:151], v148
	ds_read_b128 v[202:205], v147
	ds_read_b128 v[152:155], v152
	ds_read_b128 v[160:163], v156
	s_waitcnt lgkmcnt(0)
	v_lshlrev_b32_e32 v178, 16, v202
	v_and_b32_e32 v179, 0xffff0000, v202
	v_lshlrev_b32_e32 v176, 16, v160
	v_and_b32_e32 v177, 0xffff0000, v160
	v_mov_b32_dpp v207, v126 row_ror:1 row_mask:0xf bank_mask:0xf
	v_mov_b32_dpp v209, v127 row_ror:1 row_mask:0xf bank_mask:0xf
	v_lshlrev_b32_e32 v174, 16, v152
	v_and_b32_e32 v175, 0xffff0000, v152
	v_lshlrev_b32_e32 v168, 16, v161
	v_and_b32_e32 v169, 0xffff0000, v161
	v_lshlrev_b32_e32 v172, 16, v203
	v_and_b32_e32 v173, 0xffff0000, v203
	v_mov_b32_dpp v208, v126 row_ror:2 row_mask:0xf bank_mask:0xf
	v_mov_b32_dpp v210, v127 row_ror:2 row_mask:0xf bank_mask:0xf
	v_mov_b32_dpp v211, v128 row_ror:1 row_mask:0xf bank_mask:0xf
	v_mov_b32_dpp v213, v129 row_ror:1 row_mask:0xf bank_mask:0xf
	v_cndmask_b32_e64 v180, v207, 0, s[36:37]
	v_cndmask_b32_e64 v181, v209, 0, s[36:37]
	v_pk_fma_f32 v[216:217], v[126:127], v[176:177], v[178:179]
	v_lshlrev_b32_e32 v170, 16, v148
	v_and_b32_e32 v171, 0xffff0000, v148
	v_lshlrev_b32_e32 v166, 16, v153
	v_and_b32_e32 v167, 0xffff0000, v153
	v_mov_b32_dpp v212, v128 row_ror:2 row_mask:0xf bank_mask:0xf
	v_mov_b32_dpp v214, v129 row_ror:2 row_mask:0xf bank_mask:0xf
	v_cndmask_b32_e64 v184, 0, v208, s[38:39]
	v_cndmask_b32_e64 v185, 0, v210, s[38:39]
	v_cndmask_b32_e64 v202, v211, 0, s[36:37]
	v_cndmask_b32_e64 v203, v213, 0, s[36:37]
	v_pk_fma_f32 v[180:181], v[180:181], v[174:175], v[216:217]
	v_pk_fma_f32 v[216:217], v[128:129], v[168:169], v[172:173]
	v_lshlrev_b32_e32 v164, 16, v149
	v_and_b32_e32 v165, 0xffff0000, v149
	v_lshlrev_b32_e32 v156, 16, v150
	v_and_b32_e32 v157, 0xffff0000, v150
	v_lshlrev_b32_e32 v148, 16, v151
	v_and_b32_e32 v149, 0xffff0000, v151
	v_lshlrev_b32_e32 v158, 16, v154
	v_and_b32_e32 v159, 0xffff0000, v154
	v_lshlrev_b32_e32 v150, 16, v155
	v_and_b32_e32 v151, 0xffff0000, v155
	v_lshlrev_b32_e32 v160, 16, v162
	v_and_b32_e32 v161, 0xffff0000, v162
	v_lshlrev_b32_e32 v152, 16, v163
	v_and_b32_e32 v153, 0xffff0000, v163
	v_lshlrev_b32_e32 v162, 16, v204
	v_and_b32_e32 v163, 0xffff0000, v204
	v_lshlrev_b32_e32 v154, 16, v205
	v_and_b32_e32 v155, 0xffff0000, v205
	v_cndmask_b32_e64 v204, 0, v212, s[38:39]
	v_cndmask_b32_e64 v205, 0, v214, s[38:39]
	v_pk_fma_f32 v[180:181], v[184:185], v[170:171], v[180:181]
	s_mov_b32 s16, 0xbfb8aa3b
	v_pk_fma_f32 v[202:203], v[202:203], v[166:167], v[216:217]
	v_pk_mul_f32 v[184:185], v[180:181], s[16:17] op_sel_hi:[1,0]
	v_pk_fma_f32 v[202:203], v[204:205], v[164:165], v[202:203]
	v_exp_f32_e32 v184, v184
	v_exp_f32_e32 v185, v185
	v_pk_mul_f32 v[204:205], v[202:203], s[16:17] op_sel_hi:[1,0]
	v_exp_f32_e32 v204, v204
	v_exp_f32_e32 v205, v205
	v_pk_add_f32 v[184:185], v[184:185], 1.0 op_sel_hi:[1,0]
	v_mov_b32_dpp v197, v123 row_ror:1 row_mask:0xf bank_mask:0xf
	v_rcp_f32_e32 v184, v184
	v_rcp_f32_e32 v185, v185
	v_pk_add_f32 v[204:205], v[204:205], 1.0 op_sel_hi:[1,0]
	v_rcp_f32_e32 v204, v204
	v_rcp_f32_e32 v205, v205
	v_pk_mul_f32 v[180:181], v[180:181], v[184:185]
	v_pk_mul_f32 v[216:217], v[202:203], v[204:205]
	v_mov_b32_dpp v184, v122 row_ror:1 row_mask:0xf bank_mask:0xf
	v_mov_b32_dpp v185, v122 row_ror:2 row_mask:0xf bank_mask:0xf
	v_mov_b32_dpp v202, v123 row_ror:2 row_mask:0xf bank_mask:0xf
	v_mov_b32_dpp v203, v124 row_ror:1 row_mask:0xf bank_mask:0xf
	v_mov_b32_dpp v205, v125 row_ror:1 row_mask:0xf bank_mask:0xf
	v_cndmask_b32_e64 v218, v184, 0, s[36:37]
	v_cndmask_b32_e64 v219, v197, 0, s[36:37]
	v_pk_fma_f32 v[226:227], v[122:123], v[160:161], v[162:163]
	v_mov_b32_dpp v204, v124 row_ror:2 row_mask:0xf bank_mask:0xf
	v_mov_b32_dpp v206, v125 row_ror:2 row_mask:0xf bank_mask:0xf
	v_cndmask_b32_e64 v220, 0, v185, s[38:39]
	v_cndmask_b32_e64 v221, 0, v202, s[38:39]
	v_cndmask_b32_e64 v222, v203, 0, s[36:37]
	v_cndmask_b32_e64 v223, v205, 0, s[36:37]
	v_pk_fma_f32 v[218:219], v[218:219], v[158:159], v[226:227]
	v_pk_fma_f32 v[226:227], v[124:125], v[152:153], v[154:155]
	v_cndmask_b32_e64 v224, 0, v204, s[38:39]
	v_cndmask_b32_e64 v225, 0, v206, s[38:39]
	v_pk_fma_f32 v[218:219], v[220:221], v[156:157], v[218:219]
	v_pk_fma_f32 v[222:223], v[222:223], v[150:151], v[226:227]
	v_pk_mul_f32 v[220:221], v[218:219], s[16:17] op_sel_hi:[1,0]
	v_pk_fma_f32 v[222:223], v[224:225], v[148:149], v[222:223]
	v_exp_f32_e32 v220, v220
	v_exp_f32_e32 v221, v221
	v_pk_mul_f32 v[224:225], v[222:223], s[16:17] op_sel_hi:[1,0]
	s_lshl_b32 s5, s18, 8
	v_exp_f32_e32 v224, v224
	v_exp_f32_e32 v225, v225
	v_pk_add_f32 v[220:221], v[220:221], 1.0 op_sel_hi:[1,0]
	v_pk_mul_f32 v[226:227], v[120:121], v[216:217]
	v_rcp_f32_e32 v220, v220
	v_rcp_f32_e32 v221, v221
	v_pk_add_f32 v[224:225], v[224:225], 1.0 op_sel_hi:[1,0]
	v_readlane_b32 s16, v253, 9
	v_rcp_f32_e32 v224, v224
	v_rcp_f32_e32 v225, v225
	v_pk_mul_f32 v[216:217], v[218:219], v[220:221]
	s_add_i32 s5, s5, s34
	v_pk_mul_f32 v[180:181], v[118:119], v[180:181]
	v_pk_mul_f32 v[218:219], v[114:115], v[216:217]
	v_pk_mul_f32 v[216:217], v[222:223], v[224:225]
	v_readlane_b32 s17, v253, 10
	v_or_b32_e32 v183, s5, v136
	v_pk_mul_f32 v[220:221], v[116:117], v[216:217]
	v_cvt_pk_bf16_f32 v216, v180, v181
	v_mov_b64_e32 v[180:181], s[16:17]
	s_movk_i32 s22, 0x1600
	v_ashrrev_i32_e32 v147, 31, v146
	v_mad_i64_i32 v[180:181], s[16:17], v183, s22, v[180:181]
	v_cvt_pk_bf16_f32 v217, v226, v227
	v_cvt_pk_bf16_f32 v218, v218, v219
	v_cvt_pk_bf16_f32 v219, v220, v221
	v_lshl_add_u64 v[180:181], v[146:147], 1, v[180:181]
	global_store_dwordx4 v[180:181], v[216:219], off
	v_lshlrev_b64 v[180:181], 2, v[146:147]
	s_and_saveexec_b64 s[16:17], s[40:41]
	s_cbranch_execz .LBB0_2828
	v_readlane_b32 s20, v253, 46
	s_ashr_i32 s11, s5, 3
	v_readlane_b32 s21, v253, 47
	v_or_b32_e32 v215, s11, v138
	s_movk_i32 s18, 0x2c00
	v_mov_b64_e32 v[216:217], s[20:21]
	v_mad_i64_i32 v[216:217], s[20:21], v215, s18, v[216:217]
	v_readlane_b32 s20, v253, 48
	v_lshl_add_u64 v[216:217], v[216:217], 0, v[180:181]
	s_ashr_i32 s11, s5, 4
	v_readlane_b32 s21, v253, 49
	global_store_dwordx4 v[216:217], v[126:129], off
	global_store_dwordx4 v[216:217], v[122:125], off offset:16
	s_nop 1
	v_or_b32_e32 v124, s11, v136
	v_mov_b64_e32 v[122:123], s[20:21]
	v_mad_i64_i32 v[122:123], s[20:21], v124, s18, v[122:123]
	v_lshl_add_u64 v[122:123], v[122:123], 0, v[180:181]
	global_store_dwordx4 v[122:123], v[118:121], off
	global_store_dwordx4 v[122:123], v[114:117], off offset:16
;     __device__ __forceinline__ void operator()(const f32x4 (&acc)[2][2][4][2], const pg8::Unit& u, int wr, int wc, int fr, int fq) const {
;     ...
;                 for (int m = 0; m < 4; ++m) {
;                     const int row = row0 + ai * 128 + m * 16;
;                     float hv[8];
; #pragma unroll
;                     for (int n = 0; n < 2; ++n) {
;                         const f32x4 g = acc[ai][0][m][n], up = acc[ai][1][m][n];
;                         f32x4 c1, c2;
; #pragma unroll
;                         for (int j = 0; j < 4; ++j) {
;                             c1[j] = __int_as_float(__builtin_amdgcn_update_dpp(0, __float_as_int(g[j]), 0x121, 0xF, 0xF, false));
;                             c2[j] = __int_as_float(__builtin_amdgcn_update_dpp(0, __float_as_int(g[j]), 0x122, 0xF, 0xF, false)); }
;                         f32x4 g1v, g2v;
; #pragma unroll
;                         for (int j = 0; j < 4; ++j) { g1v[j] = fr >= 1 ? c1[j] : p1[n][j]; g2v[j] = fr >= 2 ? c2[j] : p2[n][j]; }
; #pragma unroll
;                         for (int hh = 0; hh < 2; ++hh) {
;                             const f32x2 gg = (f32x2){g[2 * hh], g[2 * hh + 1]}, a1 = (f32x2){g1v[2 * hh], g1v[2 * hh + 1]}, a2 = (f32x2){g2v[2 * hh], g2v[2 * hh + 1]};
;                             const f32x2 t0 = (f32x2){w0[n][2 * hh], w0[n][2 * hh + 1]}, t1 = (f32x2){w1[n][2 * hh], w1[n][2 * hh + 1]}, t2 = (f32x2){w2[n][2 * hh], w2[n][2 * hh + 1]};
;                             const f32x2 y = t0 * a2 + (t1 * a1 + (t2 * gg + (f32x2){bb[n][2 * hh], bb[n][2 * hh + 1]}));
;                             const f32x2 t = y * (-1.4426950408889634f);
;                             f32x2 d = (f32x2){__builtin_amdgcn_exp2f(t.x), __builtin_amdgcn_exp2f(t.y)} + 1.0f;
;                             d = (f32x2){__builtin_amdgcn_rcpf(d.x), __builtin_amdgcn_rcpf(d.y)};
;                             const f32x2 hvv = y * d * (f32x2){up[2 * hh], up[2 * hh + 1]};
;                             hv[4 * n + 2 * hh] = hvv.x; hv[4 * n + 2 * hh + 1] = hvv.y;
;                         }
;                         p1[n] = c1; p2[n] = c2;
;                     }
;                     *(u32x4*)(o0 + (size_t)row * DFF + c0) = pack8(hv);
;                     const int rr = (m & 1) * 16 + fr;
;                     if (rr >= 30 || rr < 2) {
.LBB0_2828:
	s_or_b64 exec, exec, s[16:17]
	s_nop 0
	v_mov_b32_dpp v114, v102 row_ror:1 row_mask:0xf bank_mask:0xf
	v_mov_b32_dpp v115, v102 row_ror:2 row_mask:0xf bank_mask:0xf
	v_mov_b32_dpp v116, v103 row_ror:1 row_mask:0xf bank_mask:0xf
	v_cndmask_b32_e64 v122, v114, v207, s[36:37]
	v_cndmask_b32_e64 v124, v208, v115, s[38:39]
	v_mov_b32_dpp v117, v103 row_ror:2 row_mask:0xf bank_mask:0xf
	v_cndmask_b32_e64 v123, v116, v209, s[36:37]
	v_pk_fma_f32 v[208:209], v[102:103], v[176:177], v[178:179]
	v_cndmask_b32_e64 v125, v210, v117, s[38:39]
	v_pk_fma_f32 v[122:123], v[122:123], v[174:175], v[208:209]
	s_mov_b32 s16, 0xbfb8aa3b
	v_pk_fma_f32 v[122:123], v[124:125], v[170:171], v[122:123]
	v_pk_mul_f32 v[124:125], v[122:123], s[16:17] op_sel_hi:[1,0]
	v_exp_f32_e32 v124, v124
	v_exp_f32_e32 v125, v125
	v_mov_b32_dpp v118, v104 row_ror:1 row_mask:0xf bank_mask:0xf
	v_mov_b32_dpp v120, v105 row_ror:1 row_mask:0xf bank_mask:0xf
	v_pk_add_f32 v[124:125], v[124:125], 1.0 op_sel_hi:[1,0]
	v_rcp_f32_e32 v124, v124
	v_rcp_f32_e32 v125, v125
	v_mov_b32_dpp v119, v104 row_ror:2 row_mask:0xf bank_mask:0xf
	v_mov_b32_dpp v121, v105 row_ror:2 row_mask:0xf bank_mask:0xf
	v_cndmask_b32_e64 v126, v118, v211, s[36:37]
	v_pk_mul_f32 v[122:123], v[122:123], v[124:125]
	v_cndmask_b32_e64 v127, v120, v213, s[36:37]
	v_pk_mul_f32 v[208:209], v[110:111], v[122:123]
	v_pk_fma_f32 v[110:111], v[104:105], v[168:169], v[172:173]
	v_cndmask_b32_e64 v128, v212, v119, s[38:39]
	v_cndmask_b32_e64 v129, v214, v121, s[38:39]
	v_pk_fma_f32 v[110:111], v[126:127], v[166:167], v[110:111]
	v_pk_fma_f32 v[110:111], v[128:129], v[164:165], v[110:111]
	v_pk_mul_f32 v[122:123], v[110:111], s[16:17] op_sel_hi:[1,0]
	v_mov_b32_dpp v124, v101 row_ror:1 row_mask:0xf bank_mask:0xf
	v_exp_f32_e32 v122, v122
	v_exp_f32_e32 v123, v123
	v_mov_b32_dpp v125, v101 row_ror:2 row_mask:0xf bank_mask:0xf
	v_pk_add_f32 v[122:123], v[122:123], 1.0 op_sel_hi:[1,0]
	s_nop 0
	v_rcp_f32_e32 v122, v122
	v_rcp_f32_e32 v123, v123
	s_nop 0
	v_pk_mul_f32 v[110:111], v[110:111], v[122:123]
	s_nop 0
	v_pk_mul_f32 v[126:127], v[112:113], v[110:111]
	v_mov_b32_dpp v110, v98 row_ror:1 row_mask:0xf bank_mask:0xf
	v_mov_b32_dpp v111, v98 row_ror:2 row_mask:0xf bank_mask:0xf
	v_mov_b32_dpp v112, v99 row_ror:1 row_mask:0xf bank_mask:0xf
	v_mov_b32_dpp v113, v99 row_ror:2 row_mask:0xf bank_mask:0xf
	v_mov_b32_dpp v122, v100 row_ror:1 row_mask:0xf bank_mask:0xf
	v_cndmask_b32_e64 v128, v110, v184, s[36:37]
	v_cndmask_b32_e64 v184, v185, v111, s[38:39]
	v_cndmask_b32_e64 v129, v112, v197, s[36:37]
	v_cndmask_b32_e64 v185, v202, v113, s[38:39]
	v_cndmask_b32_e64 v202, v122, v203, s[36:37]
	v_cndmask_b32_e64 v203, v124, v205, s[36:37]
	v_cndmask_b32_e64 v205, v206, v125, s[38:39]
	v_pk_fma_f32 v[206:207], v[98:99], v[160:161], v[162:163]
	v_pk_fma_f32 v[128:129], v[128:129], v[158:159], v[206:207]
	v_or_b32_e32 v197, 16, v183
	v_pk_fma_f32 v[128:129], v[184:185], v[156:157], v[128:129]
	v_mov_b32_dpp v123, v100 row_ror:2 row_mask:0xf bank_mask:0xf
	v_pk_mul_f32 v[184:185], v[128:129], s[16:17] op_sel_hi:[1,0]
	v_cndmask_b32_e64 v204, v204, v123, s[38:39]
	v_exp_f32_e32 v184, v184
	v_exp_f32_e32 v185, v185
	s_nop 0
	v_pk_add_f32 v[184:185], v[184:185], 1.0 op_sel_hi:[1,0]
	s_nop 0
	v_rcp_f32_e32 v184, v184
	v_rcp_f32_e32 v185, v185
	s_nop 0
	v_pk_mul_f32 v[128:129], v[128:129], v[184:185]
	s_nop 0
	v_pk_mul_f32 v[128:129], v[106:107], v[128:129]
	v_pk_fma_f32 v[106:107], v[100:101], v[152:153], v[154:155]
	s_nop 0
	v_pk_fma_f32 v[106:107], v[202:203], v[150:151], v[106:107]
	s_nop 0
	v_pk_fma_f32 v[106:107], v[204:205], v[148:149], v[106:107]
	s_nop 0
	v_pk_mul_f32 v[184:185], v[106:107], s[16:17] op_sel_hi:[1,0]
	v_readlane_b32 s16, v253, 9
	v_exp_f32_e32 v184, v184
	v_exp_f32_e32 v185, v185
	v_readlane_b32 s17, v253, 10
	v_pk_add_f32 v[184:185], v[184:185], 1.0 op_sel_hi:[1,0]
	s_nop 0
	v_rcp_f32_e32 v184, v184
	v_rcp_f32_e32 v185, v185
	s_nop 0
	v_pk_mul_f32 v[106:107], v[106:107], v[184:185]
	s_nop 0
	v_pk_mul_f32 v[184:185], v[108:109], v[106:107]
	v_cvt_pk_bf16_f32 v107, v126, v127
	v_mov_b64_e32 v[126:127], s[16:17]
	v_mad_i64_i32 v[126:127], s[16:17], v197, s22, v[126:127]
	v_cvt_pk_bf16_f32 v106, v208, v209
	v_cvt_pk_bf16_f32 v108, v128, v129
	v_cvt_pk_bf16_f32 v109, v184, v185
	v_lshl_add_u64 v[126:127], v[146:147], 1, v[126:127]
	global_store_dwordx4 v[126:127], v[106:109], off
	s_and_saveexec_b64 s[16:17], s[42:43]
	s_cbranch_execz .LBB0_2830
	s_ashr_i32 s20, s5, 5
	s_ashr_i32 s21, s20, 31
	v_lshl_add_u64 v[106:107], s[20:21], 2, v[140:141]
	v_readlane_b32 s20, v253, 46
	v_readlane_b32 s21, v253, 47
	s_movk_i32 s5, 0x2c00
	s_nop 0
	v_mov_b64_e32 v[108:109], s[20:21]
	v_mad_u64_u32 v[108:109], s[20:21], v106, s5, v[108:109]
	v_mad_i32_i24 v109, v107, s5, v109
	v_lshl_add_u64 v[106:107], v[146:147], 2, v[108:109]
	global_store_dwordx4 v[106:107], v[102:105], off
	global_store_dwordx4 v[106:107], v[98:101], off offset:16
;     __device__ __forceinline__ void operator()(const f32x4 (&acc)[2][2][4][2], const pg8::Unit& u, int wr, int wc, int fr, int fq) const {
;     ...
;                 for (int m = 0; m < 4; ++m) {
;                     const int row = row0 + ai * 128 + m * 16;
;                     float hv[8];
; #pragma unroll
;                     for (int n = 0; n < 2; ++n) {
;                         const f32x4 g = acc[ai][0][m][n], up = acc[ai][1][m][n];
;                         f32x4 c1, c2;
; #pragma unroll
;                         for (int j = 0; j < 4; ++j) {
;                             c1[j] = __int_as_float(__builtin_amdgcn_update_dpp(0, __float_as_int(g[j]), 0x121, 0xF, 0xF, false));
;                             c2[j] = __int_as_float(__builtin_amdgcn_update_dpp(0, __float_as_int(g[j]), 0x122, 0xF, 0xF, false)); }
;                         f32x4 g1v, g2v;
; #pragma unroll
;                         for (int j = 0; j < 4; ++j) { g1v[j] = fr >= 1 ? c1[j] : p1[n][j]; g2v[j] = fr >= 2 ? c2[j] : p2[n][j]; }
; #pragma unroll
;                         for (int hh = 0; hh < 2; ++hh) {
;                             const f32x2 gg = (f32x2){g[2 * hh], g[2 * hh + 1]}, a1 = (f32x2){g1v[2 * hh], g1v[2 * hh + 1]}, a2 = (f32x2){g2v[2 * hh], g2v[2 * hh + 1]};
;                             const f32x2 t0 = (f32x2){w0[n][2 * hh], w0[n][2 * hh + 1]}, t1 = (f32x2){w1[n][2 * hh], w1[n][2 * hh + 1]}, t2 = (f32x2){w2[n][2 * hh], w2[n][2 * hh + 1]};
;                             const f32x2 y = t0 * a2 + (t1 * a1 + (t2 * gg + (f32x2){bb[n][2 * hh], bb[n][2 * hh + 1]}));
;                             const f32x2 t = y * (-1.4426950408889634f);
;                             f32x2 d = (f32x2){__builtin_amdgcn_exp2f(t.x), __builtin_amdgcn_exp2f(t.y)} + 1.0f;
;                             d = (f32x2){__builtin_amdgcn_rcpf(d.x), __builtin_amdgcn_rcpf(d.y)};
;                             const f32x2 hvv = y * d * (f32x2){up[2 * hh], up[2 * hh + 1]};
;                             hv[4 * n + 2 * hh] = hvv.x; hv[4 * n + 2 * hh + 1] = hvv.y;
;                         }
;                         p1[n] = c1; p2[n] = c2;
;                     }
;                     *(u32x4*)(o0 + (size_t)row * DFF + c0) = pack8(hv);
;                     const int rr = (m & 1) * 16 + fr;
;                     if (rr >= 30 || rr < 2) {
.LBB0_2830:
	s_or_b64 exec, exec, s[16:17]
	v_mov_b32_dpp v106, v94 row_ror:1 row_mask:0xf bank_mask:0xf
	v_mov_b32_dpp v107, v94 row_ror:2 row_mask:0xf bank_mask:0xf
	v_mov_b32_dpp v108, v95 row_ror:1 row_mask:0xf bank_mask:0xf
	v_mov_b32_dpp v109, v95 row_ror:2 row_mask:0xf bank_mask:0xf
	v_mov_b32_dpp v126, v96 row_ror:1 row_mask:0xf bank_mask:0xf
	v_mov_b32_dpp v128, v97 row_ror:1 row_mask:0xf bank_mask:0xf
	v_cndmask_b32_e64 v98, v106, v114, s[36:37]
	v_cndmask_b32_e64 v100, v115, v107, s[38:39]
	v_cndmask_b32_e64 v99, v108, v116, s[36:37]
	v_pk_fma_f32 v[114:115], v[94:95], v[176:177], v[178:179]
	v_mov_b32_dpp v127, v96 row_ror:2 row_mask:0xf bank_mask:0xf
	v_mov_b32_dpp v129, v97 row_ror:2 row_mask:0xf bank_mask:0xf
	v_cndmask_b32_e64 v101, v117, v109, s[38:39]
	v_cndmask_b32_e64 v102, v126, v118, s[36:37]
	v_cndmask_b32_e64 v103, v128, v120, s[36:37]
	v_pk_fma_f32 v[98:99], v[98:99], v[174:175], v[114:115]
	v_pk_fma_f32 v[114:115], v[96:97], v[168:169], v[172:173]
	v_cndmask_b32_e64 v104, v119, v127, s[38:39]
	v_cndmask_b32_e64 v105, v121, v129, s[38:39]
	v_pk_fma_f32 v[98:99], v[100:101], v[170:171], v[98:99]
	s_mov_b32 s16, 0xbfb8aa3b
	v_pk_fma_f32 v[102:103], v[102:103], v[166:167], v[114:115]
	v_pk_mul_f32 v[100:101], v[98:99], s[16:17] op_sel_hi:[1,0]
	v_pk_fma_f32 v[102:103], v[104:105], v[164:165], v[102:103]
	v_exp_f32_e32 v100, v100
	v_exp_f32_e32 v101, v101
	v_pk_mul_f32 v[104:105], v[102:103], s[16:17] op_sel_hi:[1,0]
	v_pk_add_f32 v[100:101], v[100:101], 1.0 op_sel_hi:[1,0]
	v_exp_f32_e32 v104, v104
	v_exp_f32_e32 v105, v105
	v_rcp_f32_e32 v100, v100
	v_rcp_f32_e32 v101, v101
	v_pk_add_f32 v[104:105], v[104:105], 1.0 op_sel_hi:[1,0]
	s_nop 0
	v_rcp_f32_e32 v104, v104
	v_rcp_f32_e32 v105, v105
	v_pk_mul_f32 v[98:99], v[98:99], v[100:101]
	v_pk_mul_f32 v[114:115], v[86:87], v[98:99]
	v_pk_mul_f32 v[116:117], v[102:103], v[104:105]
	v_mov_b32_dpp v98, v90 row_ror:1 row_mask:0xf bank_mask:0xf
	v_mov_b32_dpp v99, v90 row_ror:2 row_mask:0xf bank_mask:0xf
	v_mov_b32_dpp v100, v91 row_ror:1 row_mask:0xf bank_mask:0xf
	v_mov_b32_dpp v102, v92 row_ror:1 row_mask:0xf bank_mask:0xf
	v_mov_b32_dpp v103, v92 row_ror:2 row_mask:0xf bank_mask:0xf
	v_mov_b32_dpp v101, v91 row_ror:2 row_mask:0xf bank_mask:0xf
	v_mov_b32_dpp v104, v93 row_ror:1 row_mask:0xf bank_mask:0xf
	v_cndmask_b32_e64 v110, v98, v110, s[36:37]
	v_cndmask_b32_e64 v118, v111, v99, s[38:39]
	v_cndmask_b32_e64 v111, v100, v112, s[36:37]
	v_cndmask_b32_e64 v112, v102, v122, s[36:37]
	v_cndmask_b32_e64 v120, v123, v103, s[38:39]
	v_pk_fma_f32 v[122:123], v[90:91], v[160:161], v[162:163]
	v_mov_b32_dpp v105, v93 row_ror:2 row_mask:0xf bank_mask:0xf
	v_cndmask_b32_e64 v119, v113, v101, s[38:39]
	v_cndmask_b32_e64 v113, v104, v124, s[36:37]
	v_pk_fma_f32 v[110:111], v[110:111], v[158:159], v[122:123]
	v_pk_fma_f32 v[122:123], v[92:93], v[152:153], v[154:155]
	v_cndmask_b32_e64 v121, v125, v105, s[38:39]
	v_pk_fma_f32 v[110:111], v[118:119], v[156:157], v[110:111]
	v_pk_fma_f32 v[112:113], v[112:113], v[150:151], v[122:123]
	v_pk_mul_f32 v[118:119], v[110:111], s[16:17] op_sel_hi:[1,0]
	v_pk_fma_f32 v[112:113], v[120:121], v[148:149], v[112:113]
	v_exp_f32_e32 v118, v118
	v_exp_f32_e32 v119, v119
	v_pk_mul_f32 v[120:121], v[112:113], s[16:17] op_sel_hi:[1,0]
	v_readlane_b32 s16, v253, 9
	v_exp_f32_e32 v120, v120
	v_exp_f32_e32 v121, v121
	v_pk_add_f32 v[118:119], v[118:119], 1.0 op_sel_hi:[1,0]
	v_pk_mul_f32 v[116:117], v[88:89], v[116:117]
	v_rcp_f32_e32 v118, v118
	v_rcp_f32_e32 v119, v119
	v_pk_add_f32 v[120:121], v[120:121], 1.0 op_sel_hi:[1,0]
	v_readlane_b32 s17, v253, 10
	v_rcp_f32_e32 v120, v120
	v_rcp_f32_e32 v121, v121
	v_pk_mul_f32 v[110:111], v[110:111], v[118:119]
	s_nop 0
	v_pk_mul_f32 v[118:119], v[82:83], v[110:111]
	v_pk_mul_f32 v[110:111], v[112:113], v[120:121]
	v_cvt_pk_bf16_f32 v113, v116, v117
	v_pk_mul_f32 v[120:121], v[84:85], v[110:111]
	v_or_b32_e32 v110, 32, v183
	v_mov_b64_e32 v[116:117], s[16:17]
	v_mad_i64_i32 v[116:117], s[16:17], v110, s22, v[116:117]
	v_cvt_pk_bf16_f32 v112, v114, v115
	v_cvt_pk_bf16_f32 v114, v118, v119
	v_cvt_pk_bf16_f32 v115, v120, v121
	v_lshl_add_u64 v[116:117], v[146:147], 1, v[116:117]
	global_store_dwordx4 v[116:117], v[112:115], off
	s_mov_b64 s[16:17], exec
	s_and_b64 s[20:21], s[16:17], s[40:41]
	v_mov_b32_e32 v241, v239
	s_mov_b64 exec, s[20:21]
	s_cbranch_execz .LBB0_2832
	v_readlane_b32 s20, v253, 46
	v_ashrrev_i32_e32 v112, 5, v110
	v_readlane_b32 s21, v253, 47
	v_lshl_or_b32 v113, v112, 2, v138
	s_movk_i32 s5, 0x2c00
	v_mov_b64_e32 v[110:111], s[20:21]
	v_mad_i64_i32 v[110:111], s[20:21], v113, s5, v[110:111]
	v_readlane_b32 s20, v253, 48
	v_lshl_add_u64 v[110:111], v[110:111], 0, v[180:181]
	v_readlane_b32 s21, v253, 49
	global_store_dwordx4 v[110:111], v[94:97], off
	global_store_dwordx4 v[110:111], v[90:93], off offset:16
	s_nop 1
	v_lshl_or_b32 v92, v112, 1, v136
	v_mov_b64_e32 v[90:91], s[20:21]
	v_mad_i64_i32 v[90:91], s[20:21], v92, s5, v[90:91]
	v_lshl_add_u64 v[90:91], v[90:91], 0, v[180:181]
	global_store_dwordx4 v[90:91], v[86:89], off
	global_store_dwordx4 v[90:91], v[82:85], off offset:16
;     __device__ __forceinline__ void operator()(const f32x4 (&acc)[2][2][4][2], const pg8::Unit& u, int wr, int wc, int fr, int fq) const {
;     ...
;                 for (int m = 0; m < 4; ++m) {
;                     const int row = row0 + ai * 128 + m * 16;
;                     float hv[8];
; #pragma unroll
;                     for (int n = 0; n < 2; ++n) {
;                         const f32x4 g = acc[ai][0][m][n], up = acc[ai][1][m][n];
;                         f32x4 c1, c2;
; #pragma unroll
;                         for (int j = 0; j < 4; ++j) {
;                             c1[j] = __int_as_float(__builtin_amdgcn_update_dpp(0, __float_as_int(g[j]), 0x121, 0xF, 0xF, false));
;                             c2[j] = __int_as_float(__builtin_amdgcn_update_dpp(0, __float_as_int(g[j]), 0x122, 0xF, 0xF, false)); }
;                         f32x4 g1v, g2v;
; #pragma unroll
;                         for (int j = 0; j < 4; ++j) { g1v[j] = fr >= 1 ? c1[j] : p1[n][j]; g2v[j] = fr >= 2 ? c2[j] : p2[n][j]; }
; #pragma unroll
;                         for (int hh = 0; hh < 2; ++hh) {
;                             const f32x2 gg = (f32x2){g[2 * hh], g[2 * hh + 1]}, a1 = (f32x2){g1v[2 * hh], g1v[2 * hh + 1]}, a2 = (f32x2){g2v[2 * hh], g2v[2 * hh + 1]};
;                             const f32x2 t0 = (f32x2){w0[n][2 * hh], w0[n][2 * hh + 1]}, t1 = (f32x2){w1[n][2 * hh], w1[n][2 * hh + 1]}, t2 = (f32x2){w2[n][2 * hh], w2[n][2 * hh + 1]};
;                             const f32x2 y = t0 * a2 + (t1 * a1 + (t2 * gg + (f32x2){bb[n][2 * hh], bb[n][2 * hh + 1]}));
;                             const f32x2 t = y * (-1.4426950408889634f);
;                             f32x2 d = (f32x2){__builtin_amdgcn_exp2f(t.x), __builtin_amdgcn_exp2f(t.y)} + 1.0f;
;                             d = (f32x2){__builtin_amdgcn_rcpf(d.x), __builtin_amdgcn_rcpf(d.y)};
;                             const f32x2 hvv = y * d * (f32x2){up[2 * hh], up[2 * hh + 1]};
;                             hv[4 * n + 2 * hh] = hvv.x; hv[4 * n + 2 * hh + 1] = hvv.y;
;                         }
;                         p1[n] = c1; p2[n] = c2;
;                     }
;                     *(u32x4*)(o0 + (size_t)row * DFF + c0) = pack8(hv);
;                     const int rr = (m & 1) * 16 + fr;
;                     if (rr >= 30 || rr < 2) {
.LBB0_2832:
	s_or_b64 exec, exec, s[16:17]
	s_nop 0
	v_mov_b32_dpp v82, v70 row_ror:1 row_mask:0xf bank_mask:0xf
	v_mov_b32_dpp v83, v70 row_ror:2 row_mask:0xf bank_mask:0xf
	v_mov_b32_dpp v85, v71 row_ror:1 row_mask:0xf bank_mask:0xf
	v_mov_b32_dpp v86, v71 row_ror:2 row_mask:0xf bank_mask:0xf
	v_mov_b32_dpp v87, v72 row_ror:1 row_mask:0xf bank_mask:0xf
	v_mov_b32_dpp v89, v73 row_ror:1 row_mask:0xf bank_mask:0xf
	v_mov_b32_dpp v90, v73 row_ror:2 row_mask:0xf bank_mask:0xf
	v_cndmask_b32_e64 v82, v82, v106, s[36:37]
	v_cndmask_b32_e64 v84, v107, v83, s[38:39]
	v_cndmask_b32_e64 v83, v85, v108, s[36:37]
	v_cndmask_b32_e64 v85, v109, v86, s[38:39]
	v_cndmask_b32_e64 v86, v87, v126, s[36:37]
	v_cndmask_b32_e64 v87, v89, v128, s[36:37]
	v_cndmask_b32_e64 v89, v129, v90, s[38:39]
	v_pk_fma_f32 v[90:91], v[70:71], v[176:177], v[178:179]
	s_mov_b32 s16, 0xbfb8aa3b
	v_pk_fma_f32 v[82:83], v[82:83], v[174:175], v[90:91]
	v_pk_fma_f32 v[82:83], v[84:85], v[170:171], v[82:83]
	v_pk_mul_f32 v[84:85], v[82:83], s[16:17] op_sel_hi:[1,0]
	v_mov_b32_dpp v88, v72 row_ror:2 row_mask:0xf bank_mask:0xf
	v_exp_f32_e32 v84, v84
	v_exp_f32_e32 v85, v85
	v_cndmask_b32_e64 v88, v127, v88, s[38:39]
	v_mov_b32_dpp v90, v69 row_ror:2 row_mask:0xf bank_mask:0xf
	v_pk_add_f32 v[84:85], v[84:85], 1.0 op_sel_hi:[1,0]
	s_nop 0
	v_rcp_f32_e32 v84, v84
	v_rcp_f32_e32 v85, v85
	s_nop 0
	v_pk_mul_f32 v[82:83], v[82:83], v[84:85]
	s_nop 0
	v_pk_mul_f32 v[78:79], v[78:79], v[82:83]
	v_pk_fma_f32 v[82:83], v[72:73], v[168:169], v[172:173]
	s_nop 0
	v_pk_fma_f32 v[82:83], v[86:87], v[166:167], v[82:83]
	v_pk_fma_f32 v[82:83], v[88:89], v[164:165], v[82:83]
	v_pk_mul_f32 v[84:85], v[82:83], s[16:17] op_sel_hi:[1,0]
	v_exp_f32_e32 v84, v84
	v_exp_f32_e32 v85, v85
	v_mov_b32_dpp v86, v67 row_ror:2 row_mask:0xf bank_mask:0xf
	v_mov_b32_dpp v87, v68 row_ror:1 row_mask:0xf bank_mask:0xf
	v_mov_b32_dpp v89, v69 row_ror:1 row_mask:0xf bank_mask:0xf
	v_pk_add_f32 v[84:85], v[84:85], 1.0 op_sel_hi:[1,0]
	v_rcp_f32_e32 v84, v84
	v_rcp_f32_e32 v85, v85
	v_mov_b32_dpp v88, v68 row_ror:2 row_mask:0xf bank_mask:0xf
	v_cndmask_b32_e64 v88, v103, v88, s[38:39]
	v_pk_mul_f32 v[82:83], v[82:83], v[84:85]
	s_nop 0
	v_pk_mul_f32 v[80:81], v[80:81], v[82:83]
	v_mov_b32_dpp v82, v66 row_ror:1 row_mask:0xf bank_mask:0xf
	v_mov_b32_dpp v83, v66 row_ror:2 row_mask:0xf bank_mask:0xf
	v_mov_b32_dpp v85, v67 row_ror:1 row_mask:0xf bank_mask:0xf
	v_cndmask_b32_e64 v82, v82, v98, s[36:37]
	v_cndmask_b32_e64 v84, v99, v83, s[38:39]
	v_cndmask_b32_e64 v83, v85, v100, s[36:37]
	v_cndmask_b32_e64 v85, v101, v86, s[38:39]
	v_cndmask_b32_e64 v86, v87, v102, s[36:37]
	v_cndmask_b32_e64 v87, v89, v104, s[36:37]
	v_cndmask_b32_e64 v89, v105, v90, s[38:39]
	v_pk_fma_f32 v[90:91], v[66:67], v[160:161], v[162:163]
	s_nop 0
	v_pk_fma_f32 v[82:83], v[82:83], v[158:159], v[90:91]
	s_nop 0
	v_pk_fma_f32 v[82:83], v[84:85], v[156:157], v[82:83]
	s_nop 0
	v_pk_mul_f32 v[84:85], v[82:83], s[16:17] op_sel_hi:[1,0]
	s_nop 0
	v_exp_f32_e32 v84, v84
	v_exp_f32_e32 v85, v85
	s_nop 0
	v_pk_add_f32 v[84:85], v[84:85], 1.0 op_sel_hi:[1,0]
	s_nop 0
	v_rcp_f32_e32 v84, v84
	v_rcp_f32_e32 v85, v85
	s_nop 0
	v_pk_mul_f32 v[82:83], v[82:83], v[84:85]
	s_nop 0
	v_pk_mul_f32 v[82:83], v[74:75], v[82:83]
	v_pk_fma_f32 v[74:75], v[68:69], v[152:153], v[154:155]
	s_nop 0
	v_pk_fma_f32 v[74:75], v[86:87], v[150:151], v[74:75]
	s_nop 0
	v_pk_fma_f32 v[74:75], v[88:89], v[148:149], v[74:75]
	s_nop 0
	v_pk_mul_f32 v[84:85], v[74:75], s[16:17] op_sel_hi:[1,0]
	v_readlane_b32 s16, v253, 9
	v_exp_f32_e32 v84, v84
	v_exp_f32_e32 v85, v85
	v_readlane_b32 s17, v253, 10
	v_pk_add_f32 v[84:85], v[84:85], 1.0 op_sel_hi:[1,0]
	s_nop 0
	v_rcp_f32_e32 v84, v84
	v_rcp_f32_e32 v85, v85
	s_nop 0
	v_pk_mul_f32 v[74:75], v[74:75], v[84:85]
	s_nop 0
	v_pk_mul_f32 v[84:85], v[76:77], v[74:75]
	v_or_b32_e32 v74, 48, v183
	v_cvt_pk_bf16_f32 v77, v80, v81
	v_mov_b64_e32 v[80:81], s[16:17]
	v_mad_i64_i32 v[80:81], s[16:17], v74, s22, v[80:81]
	v_cvt_pk_bf16_f32 v76, v78, v79
	v_cvt_pk_bf16_f32 v78, v82, v83
	v_cvt_pk_bf16_f32 v79, v84, v85
	v_lshl_add_u64 v[80:81], v[146:147], 1, v[80:81]
	global_store_dwordx4 v[80:81], v[76:79], off
	s_and_saveexec_b64 s[16:17], s[42:43]
	s_cbranch_execz .LBB0_2834
	v_ashrrev_i32_e32 v74, 5, v74
	v_readlane_b32 s20, v253, 46
	v_ashrrev_i32_e32 v75, 31, v74
	v_readlane_b32 s21, v253, 47
	v_lshl_add_u64 v[74:75], v[74:75], 2, v[140:141]
	s_movk_i32 s5, 0x2c00
	v_mov_b64_e32 v[76:77], s[20:21]
	v_mad_u64_u32 v[76:77], s[20:21], v74, s5, v[76:77]
	v_mad_i32_i24 v77, v75, s5, v77
	v_lshl_add_u64 v[74:75], v[146:147], 2, v[76:77]
	global_store_dwordx4 v[74:75], v[70:73], off
	global_store_dwordx4 v[74:75], v[66:69], off offset:16
;     __device__ __forceinline__ void operator()(const f32x4 (&acc)[2][2][4][2], const pg8::Unit& u, int wr, int wc, int fr, int fq) const {
;     ...
;             for (int ai = 0; ai < 2; ++ai) {
;                 f32x4 p1[2] = {(f32x4){0.f, 0.f, 0.f, 0.f}, (f32x4){0.f, 0.f, 0.f, 0.f}}, p2[2] = {(f32x4){0.f, 0.f, 0.f, 0.f}, (f32x4){0.f, 0.f, 0.f, 0.f}};
; #pragma unroll
;                 for (int m = 0; m < 4; ++m) {
;                     const int row = row0 + ai * 128 + m * 16;
;                     float hv[8];
; #pragma unroll
;                     for (int n = 0; n < 2; ++n) {
;                         const f32x4 g = acc[ai][0][m][n], up = acc[ai][1][m][n];
;                         f32x4 c1, c2;
; #pragma unroll
;                         for (int j = 0; j < 4; ++j) {
;                             c1[j] = __int_as_float(__builtin_amdgcn_update_dpp(0, __float_as_int(g[j]), 0x121, 0xF, 0xF, false));
;                             c2[j] = __int_as_float(__builtin_amdgcn_update_dpp(0, __float_as_int(g[j]), 0x122, 0xF, 0xF, false)); }
;                         f32x4 g1v, g2v;
; #pragma unroll
;                         for (int j = 0; j < 4; ++j) { g1v[j] = fr >= 1 ? c1[j] : p1[n][j]; g2v[j] = fr >= 2 ? c2[j] : p2[n][j]; }
; #pragma unroll
;                         for (int hh = 0; hh < 2; ++hh) {
;                             const f32x2 gg = (f32x2){g[2 * hh], g[2 * hh + 1]}, a1 = (f32x2){g1v[2 * hh], g1v[2 * hh + 1]}, a2 = (f32x2){g2v[2 * hh], g2v[2 * hh + 1]};
;                             const f32x2 t0 = (f32x2){w0[n][2 * hh], w0[n][2 * hh + 1]}, t1 = (f32x2){w1[n][2 * hh], w1[n][2 * hh + 1]}, t2 = (f32x2){w2[n][2 * hh], w2[n][2 * hh + 1]};
;                             const f32x2 y = t0 * a2 + (t1 * a1 + (t2 * gg + (f32x2){bb[n][2 * hh], bb[n][2 * hh + 1]}));
;                             const f32x2 t = y * (-1.4426950408889634f);
;                             f32x2 d = (f32x2){__builtin_amdgcn_exp2f(t.x), __builtin_amdgcn_exp2f(t.y)} + 1.0f;
;                             d = (f32x2){__builtin_amdgcn_rcpf(d.x), __builtin_amdgcn_rcpf(d.y)};
;                             const f32x2 hvv = y * d * (f32x2){up[2 * hh], up[2 * hh + 1]};
;                             hv[4 * n + 2 * hh] = hvv.x; hv[4 * n + 2 * hh + 1] = hvv.y;
;                         }
;                         p1[n] = c1; p2[n] = c2;
;                     }
.LBB0_2834:
	s_or_b64 exec, exec, s[16:17]
	v_mov_b32_dpp v74, v62 row_ror:1 row_mask:0xf bank_mask:0xf
	v_mov_b32_dpp v76, v63 row_ror:1 row_mask:0xf bank_mask:0xf
	v_mov_b32_dpp v75, v62 row_ror:2 row_mask:0xf bank_mask:0xf
	v_cndmask_b32_e64 v66, v74, 0, s[36:37]
	v_mov_b32_dpp v77, v63 row_ror:2 row_mask:0xf bank_mask:0xf
	v_cndmask_b32_e64 v67, v76, 0, s[36:37]
	v_pk_fma_f32 v[82:83], v[62:63], v[176:177], v[178:179]
	v_cndmask_b32_e64 v68, 0, v75, s[38:39]
	v_cndmask_b32_e64 v69, 0, v77, s[38:39]
	v_pk_fma_f32 v[66:67], v[66:67], v[174:175], v[82:83]
	v_mov_b32_dpp v78, v64 row_ror:1 row_mask:0xf bank_mask:0xf
	v_mov_b32_dpp v80, v65 row_ror:1 row_mask:0xf bank_mask:0xf
	v_pk_fma_f32 v[66:67], v[68:69], v[170:171], v[66:67]
	s_mov_b32 s16, 0xbfb8aa3b
	v_mov_b32_dpp v79, v64 row_ror:2 row_mask:0xf bank_mask:0xf
	v_mov_b32_dpp v81, v65 row_ror:2 row_mask:0xf bank_mask:0xf
	v_cndmask_b32_e64 v70, v78, 0, s[36:37]
	v_cndmask_b32_e64 v71, v80, 0, s[36:37]
	v_pk_mul_f32 v[68:69], v[66:67], s[16:17] op_sel_hi:[1,0]
	v_pk_fma_f32 v[82:83], v[64:65], v[168:169], v[172:173]
	v_cndmask_b32_e64 v72, 0, v79, s[38:39]
	v_cndmask_b32_e64 v73, 0, v81, s[38:39]
	v_exp_f32_e32 v68, v68
	v_exp_f32_e32 v69, v69
	v_pk_fma_f32 v[70:71], v[70:71], v[166:167], v[82:83]
	v_pk_fma_f32 v[96:97], v[58:59], v[160:161], v[162:163]
	v_pk_fma_f32 v[70:71], v[72:73], v[164:165], v[70:71]
	v_pk_add_f32 v[68:69], v[68:69], 1.0 op_sel_hi:[1,0]
	v_pk_mul_f32 v[72:73], v[70:71], s[16:17] op_sel_hi:[1,0]
	v_rcp_f32_e32 v68, v68
	v_exp_f32_e32 v72, v72
	v_exp_f32_e32 v73, v73
	v_rcp_f32_e32 v69, v69
	v_add_u32_e32 v82, 0x80, v183
	v_pk_add_f32 v[72:73], v[72:73], 1.0 op_sel_hi:[1,0]
	s_nop 0
	v_rcp_f32_e32 v72, v72
	v_rcp_f32_e32 v73, v73
	v_pk_mul_f32 v[66:67], v[66:67], v[68:69]
	v_pk_mul_f32 v[84:85], v[54:55], v[66:67]
	v_mov_b32_dpp v68, v59 row_ror:1 row_mask:0xf bank_mask:0xf
	v_mov_b32_dpp v66, v58 row_ror:1 row_mask:0xf bank_mask:0xf
	v_pk_mul_f32 v[86:87], v[70:71], v[72:73]
	v_mov_b32_dpp v67, v58 row_ror:2 row_mask:0xf bank_mask:0xf
	v_mov_b32_dpp v69, v59 row_ror:2 row_mask:0xf bank_mask:0xf
	v_cndmask_b32_e64 v88, v66, 0, s[36:37]
	v_cndmask_b32_e64 v89, v68, 0, s[36:37]
	v_mov_b32_dpp v70, v60 row_ror:1 row_mask:0xf bank_mask:0xf
	v_mov_b32_dpp v72, v61 row_ror:1 row_mask:0xf bank_mask:0xf
	v_cndmask_b32_e64 v90, 0, v67, s[38:39]
	v_cndmask_b32_e64 v91, 0, v69, s[38:39]
	v_pk_fma_f32 v[88:89], v[88:89], v[158:159], v[96:97]
	v_mov_b32_dpp v71, v60 row_ror:2 row_mask:0xf bank_mask:0xf
	v_mov_b32_dpp v73, v61 row_ror:2 row_mask:0xf bank_mask:0xf
	v_cndmask_b32_e64 v92, v70, 0, s[36:37]
	v_cndmask_b32_e64 v93, v72, 0, s[36:37]
	v_pk_fma_f32 v[88:89], v[90:91], v[156:157], v[88:89]
	v_pk_fma_f32 v[96:97], v[60:61], v[152:153], v[154:155]
	v_cndmask_b32_e64 v94, 0, v71, s[38:39]
	v_cndmask_b32_e64 v95, 0, v73, s[38:39]
	v_pk_mul_f32 v[90:91], v[88:89], s[16:17] op_sel_hi:[1,0]
	v_pk_fma_f32 v[92:93], v[92:93], v[150:151], v[96:97]
	v_exp_f32_e32 v90, v90
	v_exp_f32_e32 v91, v91
	v_pk_fma_f32 v[92:93], v[94:95], v[148:149], v[92:93]
	v_pk_mul_f32 v[86:87], v[56:57], v[86:87]
	v_pk_mul_f32 v[94:95], v[92:93], s[16:17] op_sel_hi:[1,0]
	v_pk_add_f32 v[90:91], v[90:91], 1.0 op_sel_hi:[1,0]
	v_exp_f32_e32 v94, v94
	v_exp_f32_e32 v95, v95
	v_rcp_f32_e32 v90, v90
	v_rcp_f32_e32 v91, v91
	v_readlane_b32 s16, v253, 9
	v_pk_add_f32 v[94:95], v[94:95], 1.0 op_sel_hi:[1,0]
	v_readlane_b32 s17, v253, 10
	v_rcp_f32_e32 v94, v94
	v_rcp_f32_e32 v95, v95
	v_pk_mul_f32 v[88:89], v[88:89], v[90:91]
	v_cvt_pk_bf16_f32 v84, v84, v85
	v_pk_mul_f32 v[88:89], v[50:51], v[88:89]
	v_pk_mul_f32 v[90:91], v[92:93], v[94:95]
	v_cvt_pk_bf16_f32 v85, v86, v87
	v_cvt_pk_bf16_f32 v86, v88, v89
	v_mov_b64_e32 v[88:89], s[16:17]
	v_pk_mul_f32 v[90:91], v[52:53], v[90:91]
	v_mad_i64_i32 v[88:89], s[16:17], v82, s22, v[88:89]
	v_cvt_pk_bf16_f32 v87, v90, v91
	v_lshl_add_u64 v[88:89], v[146:147], 1, v[88:89]
	global_store_dwordx4 v[88:89], v[84:87], off
	s_and_saveexec_b64 s[16:17], s[40:41]
	s_cbranch_execz .LBB0_2836
	v_readlane_b32 s20, v253, 46
	v_ashrrev_i32_e32 v84, 5, v82
	v_readlane_b32 s21, v253, 47
	v_lshl_or_b32 v85, v84, 2, v138
	s_movk_i32 s5, 0x2c00
	v_mov_b64_e32 v[82:83], s[20:21]
	v_mad_i64_i32 v[82:83], s[20:21], v85, s5, v[82:83]
	v_readlane_b32 s20, v253, 48
	v_lshl_add_u64 v[82:83], v[82:83], 0, v[180:181]
	v_readlane_b32 s21, v253, 49
	global_store_dwordx4 v[82:83], v[62:65], off
	global_store_dwordx4 v[82:83], v[58:61], off offset:16
	s_nop 1
	v_lshl_or_b32 v60, v84, 1, v136
	v_mov_b64_e32 v[58:59], s[20:21]
	v_mad_i64_i32 v[58:59], s[20:21], v60, s5, v[58:59]
	v_lshl_add_u64 v[58:59], v[58:59], 0, v[180:181]
	global_store_dwordx4 v[58:59], v[54:57], off
	global_store_dwordx4 v[58:59], v[50:53], off offset:16
;     __device__ __forceinline__ void operator()(const f32x4 (&acc)[2][2][4][2], const pg8::Unit& u, int wr, int wc, int fr, int fq) const {
;     ...
;                 for (int m = 0; m < 4; ++m) {
;                     const int row = row0 + ai * 128 + m * 16;
;                     float hv[8];
; #pragma unroll
;                     for (int n = 0; n < 2; ++n) {
;                         const f32x4 g = acc[ai][0][m][n], up = acc[ai][1][m][n];
;                         f32x4 c1, c2;
; #pragma unroll
;                         for (int j = 0; j < 4; ++j) {
;                             c1[j] = __int_as_float(__builtin_amdgcn_update_dpp(0, __float_as_int(g[j]), 0x121, 0xF, 0xF, false));
;                             c2[j] = __int_as_float(__builtin_amdgcn_update_dpp(0, __float_as_int(g[j]), 0x122, 0xF, 0xF, false)); }
;                         f32x4 g1v, g2v;
; #pragma unroll
;                         for (int j = 0; j < 4; ++j) { g1v[j] = fr >= 1 ? c1[j] : p1[n][j]; g2v[j] = fr >= 2 ? c2[j] : p2[n][j]; }
; #pragma unroll
;                         for (int hh = 0; hh < 2; ++hh) {
;                             const f32x2 gg = (f32x2){g[2 * hh], g[2 * hh + 1]}, a1 = (f32x2){g1v[2 * hh], g1v[2 * hh + 1]}, a2 = (f32x2){g2v[2 * hh], g2v[2 * hh + 1]};
;                             const f32x2 t0 = (f32x2){w0[n][2 * hh], w0[n][2 * hh + 1]}, t1 = (f32x2){w1[n][2 * hh], w1[n][2 * hh + 1]}, t2 = (f32x2){w2[n][2 * hh], w2[n][2 * hh + 1]};
;                             const f32x2 y = t0 * a2 + (t1 * a1 + (t2 * gg + (f32x2){bb[n][2 * hh], bb[n][2 * hh + 1]}));
;                             const f32x2 t = y * (-1.4426950408889634f);
;                             f32x2 d = (f32x2){__builtin_amdgcn_exp2f(t.x), __builtin_amdgcn_exp2f(t.y)} + 1.0f;
;                             d = (f32x2){__builtin_amdgcn_rcpf(d.x), __builtin_amdgcn_rcpf(d.y)};
;                             const f32x2 hvv = y * d * (f32x2){up[2 * hh], up[2 * hh + 1]};
;                             hv[4 * n + 2 * hh] = hvv.x; hv[4 * n + 2 * hh + 1] = hvv.y;
;                         }
;                         p1[n] = c1; p2[n] = c2;
;                     }
;                     *(u32x4*)(o0 + (size_t)row * DFF + c0) = pack8(hv);
;                     const int rr = (m & 1) * 16 + fr;
;                     if (rr >= 30 || rr < 2) {
.LBB0_2836:
	s_or_b64 exec, exec, s[16:17]
	s_nop 0
	v_mov_b32_dpp v50, v38 row_ror:1 row_mask:0xf bank_mask:0xf
	v_mov_b32_dpp v51, v38 row_ror:2 row_mask:0xf bank_mask:0xf
	v_mov_b32_dpp v52, v39 row_ror:1 row_mask:0xf bank_mask:0xf
	v_cndmask_b32_e64 v58, v50, v74, s[36:37]
	v_cndmask_b32_e64 v60, v75, v51, s[38:39]
	v_mov_b32_dpp v53, v39 row_ror:2 row_mask:0xf bank_mask:0xf
	v_cndmask_b32_e64 v59, v52, v76, s[36:37]
	v_pk_fma_f32 v[74:75], v[38:39], v[176:177], v[178:179]
	v_cndmask_b32_e64 v61, v77, v53, s[38:39]
	v_pk_fma_f32 v[58:59], v[58:59], v[174:175], v[74:75]
	s_mov_b32 s16, 0xbfb8aa3b
	v_pk_fma_f32 v[58:59], v[60:61], v[170:171], v[58:59]
	v_pk_mul_f32 v[60:61], v[58:59], s[16:17] op_sel_hi:[1,0]
	v_exp_f32_e32 v60, v60
	v_exp_f32_e32 v61, v61
	v_mov_b32_dpp v54, v40 row_ror:1 row_mask:0xf bank_mask:0xf
	v_mov_b32_dpp v56, v41 row_ror:1 row_mask:0xf bank_mask:0xf
	v_pk_add_f32 v[60:61], v[60:61], 1.0 op_sel_hi:[1,0]
	v_rcp_f32_e32 v60, v60
	v_rcp_f32_e32 v61, v61
	v_mov_b32_dpp v55, v40 row_ror:2 row_mask:0xf bank_mask:0xf
	v_mov_b32_dpp v57, v41 row_ror:2 row_mask:0xf bank_mask:0xf
	v_cndmask_b32_e64 v62, v54, v78, s[36:37]
	v_pk_mul_f32 v[58:59], v[58:59], v[60:61]
	v_cndmask_b32_e64 v63, v56, v80, s[36:37]
	v_pk_mul_f32 v[74:75], v[46:47], v[58:59]
	v_pk_fma_f32 v[46:47], v[40:41], v[168:169], v[172:173]
	v_cndmask_b32_e64 v64, v79, v55, s[38:39]
	v_cndmask_b32_e64 v65, v81, v57, s[38:39]
	v_pk_fma_f32 v[46:47], v[62:63], v[166:167], v[46:47]
	v_pk_fma_f32 v[46:47], v[64:65], v[164:165], v[46:47]
	v_pk_mul_f32 v[58:59], v[46:47], s[16:17] op_sel_hi:[1,0]
	v_mov_b32_dpp v60, v37 row_ror:1 row_mask:0xf bank_mask:0xf
	v_exp_f32_e32 v58, v58
	v_exp_f32_e32 v59, v59
	v_mov_b32_dpp v61, v37 row_ror:2 row_mask:0xf bank_mask:0xf
	v_pk_add_f32 v[58:59], v[58:59], 1.0 op_sel_hi:[1,0]
	s_nop 0
	v_rcp_f32_e32 v58, v58
	v_rcp_f32_e32 v59, v59
	s_nop 0
	v_pk_mul_f32 v[46:47], v[46:47], v[58:59]
	s_nop 0
	v_pk_mul_f32 v[64:65], v[48:49], v[46:47]
	v_mov_b32_dpp v46, v34 row_ror:1 row_mask:0xf bank_mask:0xf
	v_mov_b32_dpp v47, v34 row_ror:2 row_mask:0xf bank_mask:0xf
	v_mov_b32_dpp v48, v35 row_ror:1 row_mask:0xf bank_mask:0xf
	v_mov_b32_dpp v49, v35 row_ror:2 row_mask:0xf bank_mask:0xf
	v_mov_b32_dpp v58, v36 row_ror:1 row_mask:0xf bank_mask:0xf
	v_mov_b32_dpp v59, v36 row_ror:2 row_mask:0xf bank_mask:0xf
	v_cndmask_b32_e64 v62, v46, v66, s[36:37]
	v_cndmask_b32_e64 v66, v67, v47, s[38:39]
	v_cndmask_b32_e64 v63, v48, v68, s[36:37]
	v_cndmask_b32_e64 v67, v69, v49, s[38:39]
	v_cndmask_b32_e64 v68, v58, v70, s[36:37]
	v_cndmask_b32_e64 v70, v71, v59, s[38:39]
	v_cndmask_b32_e64 v69, v60, v72, s[36:37]
	v_cndmask_b32_e64 v71, v73, v61, s[38:39]
	v_pk_fma_f32 v[72:73], v[34:35], v[160:161], v[162:163]
	s_nop 0
	v_pk_fma_f32 v[62:63], v[62:63], v[158:159], v[72:73]
	s_nop 0
	v_pk_fma_f32 v[62:63], v[66:67], v[156:157], v[62:63]
	s_nop 0
	v_pk_mul_f32 v[66:67], v[62:63], s[16:17] op_sel_hi:[1,0]
	s_nop 0
	v_exp_f32_e32 v66, v66
	v_exp_f32_e32 v67, v67
	s_nop 0
	v_pk_add_f32 v[66:67], v[66:67], 1.0 op_sel_hi:[1,0]
	s_nop 0
	v_rcp_f32_e32 v66, v66
	v_rcp_f32_e32 v67, v67
	s_nop 0
	v_pk_mul_f32 v[62:63], v[62:63], v[66:67]
	s_nop 0
	v_pk_mul_f32 v[66:67], v[42:43], v[62:63]
	v_pk_fma_f32 v[42:43], v[36:37], v[152:153], v[154:155]
	s_nop 0
	v_pk_fma_f32 v[42:43], v[68:69], v[150:151], v[42:43]
	s_nop 0
	v_pk_fma_f32 v[42:43], v[70:71], v[148:149], v[42:43]
	s_nop 0
	v_pk_mul_f32 v[62:63], v[42:43], s[16:17] op_sel_hi:[1,0]
	v_readlane_b32 s16, v253, 9
	v_exp_f32_e32 v62, v62
	v_exp_f32_e32 v63, v63
	v_readlane_b32 s17, v253, 10
	v_pk_add_f32 v[62:63], v[62:63], 1.0 op_sel_hi:[1,0]
	s_nop 0
	v_rcp_f32_e32 v62, v62
	v_rcp_f32_e32 v63, v63
	s_nop 0
	v_pk_mul_f32 v[42:43], v[42:43], v[62:63]
	s_nop 0
	v_pk_mul_f32 v[44:45], v[44:45], v[42:43]
	v_add_u32_e32 v42, 0x90, v183
	v_cvt_pk_bf16_f32 v63, v64, v65
	v_cvt_pk_bf16_f32 v65, v44, v45
	v_mov_b64_e32 v[44:45], s[16:17]
	v_mad_i64_i32 v[44:45], s[16:17], v42, s22, v[44:45]
	v_cvt_pk_bf16_f32 v62, v74, v75
	v_cvt_pk_bf16_f32 v64, v66, v67
	v_lshl_add_u64 v[44:45], v[146:147], 1, v[44:45]
	global_store_dwordx4 v[44:45], v[62:65], off
	s_and_saveexec_b64 s[16:17], s[42:43]
	s_cbranch_execz .LBB0_2838
	v_ashrrev_i32_e32 v42, 5, v42
	v_readlane_b32 s20, v253, 46
	v_ashrrev_i32_e32 v43, 31, v42
	v_readlane_b32 s21, v253, 47
	v_lshl_add_u64 v[42:43], v[42:43], 2, v[140:141]
	s_movk_i32 s5, 0x2c00
	v_mov_b64_e32 v[44:45], s[20:21]
	v_mad_u64_u32 v[44:45], s[20:21], v42, s5, v[44:45]
	v_mad_i32_i24 v45, v43, s5, v45
	v_lshl_add_u64 v[42:43], v[146:147], 2, v[44:45]
	global_store_dwordx4 v[42:43], v[38:41], off
	global_store_dwordx4 v[42:43], v[34:37], off offset:16
;     __device__ __forceinline__ void operator()(const f32x4 (&acc)[2][2][4][2], const pg8::Unit& u, int wr, int wc, int fr, int fq) const {
;     ...
;                 for (int m = 0; m < 4; ++m) {
;                     const int row = row0 + ai * 128 + m * 16;
;                     float hv[8];
; #pragma unroll
;                     for (int n = 0; n < 2; ++n) {
;                         const f32x4 g = acc[ai][0][m][n], up = acc[ai][1][m][n];
;                         f32x4 c1, c2;
; #pragma unroll
;                         for (int j = 0; j < 4; ++j) {
;                             c1[j] = __int_as_float(__builtin_amdgcn_update_dpp(0, __float_as_int(g[j]), 0x121, 0xF, 0xF, false));
;                             c2[j] = __int_as_float(__builtin_amdgcn_update_dpp(0, __float_as_int(g[j]), 0x122, 0xF, 0xF, false)); }
;                         f32x4 g1v, g2v;
; #pragma unroll
;                         for (int j = 0; j < 4; ++j) { g1v[j] = fr >= 1 ? c1[j] : p1[n][j]; g2v[j] = fr >= 2 ? c2[j] : p2[n][j]; }
; #pragma unroll
;                         for (int hh = 0; hh < 2; ++hh) {
;                             const f32x2 gg = (f32x2){g[2 * hh], g[2 * hh + 1]}, a1 = (f32x2){g1v[2 * hh], g1v[2 * hh + 1]}, a2 = (f32x2){g2v[2 * hh], g2v[2 * hh + 1]};
;                             const f32x2 t0 = (f32x2){w0[n][2 * hh], w0[n][2 * hh + 1]}, t1 = (f32x2){w1[n][2 * hh], w1[n][2 * hh + 1]}, t2 = (f32x2){w2[n][2 * hh], w2[n][2 * hh + 1]};
;                             const f32x2 y = t0 * a2 + (t1 * a1 + (t2 * gg + (f32x2){bb[n][2 * hh], bb[n][2 * hh + 1]}));
;                             const f32x2 t = y * (-1.4426950408889634f);
;                             f32x2 d = (f32x2){__builtin_amdgcn_exp2f(t.x), __builtin_amdgcn_exp2f(t.y)} + 1.0f;
;                             d = (f32x2){__builtin_amdgcn_rcpf(d.x), __builtin_amdgcn_rcpf(d.y)};
;                             const f32x2 hvv = y * d * (f32x2){up[2 * hh], up[2 * hh + 1]};
;                             hv[4 * n + 2 * hh] = hvv.x; hv[4 * n + 2 * hh + 1] = hvv.y;
;                         }
;                         p1[n] = c1; p2[n] = c2;
;                     }
;                     *(u32x4*)(o0 + (size_t)row * DFF + c0) = pack8(hv);
;                     const int rr = (m & 1) * 16 + fr;
;                     if (rr >= 30 || rr < 2) {
.LBB0_2838:
	s_or_b64 exec, exec, s[16:17]
	s_nop 0
	v_mov_b32_dpp v34, v30 row_ror:1 row_mask:0xf bank_mask:0xf
	v_mov_b32_dpp v36, v30 row_ror:2 row_mask:0xf bank_mask:0xf
	v_mov_b32_dpp v38, v31 row_ror:1 row_mask:0xf bank_mask:0xf
	v_mov_b32_dpp v40, v31 row_ror:2 row_mask:0xf bank_mask:0xf
	v_mov_b32_dpp v42, v32 row_ror:1 row_mask:0xf bank_mask:0xf
	v_mov_b32_dpp v44, v32 row_ror:2 row_mask:0xf bank_mask:0xf
	v_mov_b32_dpp v62, v33 row_ror:1 row_mask:0xf bank_mask:0xf
	v_mov_b32_dpp v63, v33 row_ror:2 row_mask:0xf bank_mask:0xf
	v_cndmask_b32_e64 v50, v34, v50, s[36:37]
	v_cndmask_b32_e64 v64, v51, v36, s[38:39]
	v_cndmask_b32_e64 v51, v38, v52, s[36:37]
	v_cndmask_b32_e64 v65, v53, v40, s[38:39]
	v_cndmask_b32_e64 v52, v42, v54, s[36:37]
	v_cndmask_b32_e64 v54, v55, v44, s[38:39]
	v_cndmask_b32_e64 v53, v62, v56, s[36:37]
	v_cndmask_b32_e64 v55, v57, v63, s[38:39]
	v_pk_fma_f32 v[56:57], v[30:31], v[176:177], v[178:179]
	s_mov_b32 s16, 0xbfb8aa3b
	v_pk_fma_f32 v[50:51], v[50:51], v[174:175], v[56:57]
	v_pk_fma_f32 v[50:51], v[64:65], v[170:171], v[50:51]
	v_pk_fma_f32 v[64:65], v[32:33], v[168:169], v[172:173]
	v_pk_mul_f32 v[56:57], v[50:51], s[16:17] op_sel_hi:[1,0]
	v_pk_fma_f32 v[52:53], v[52:53], v[166:167], v[64:65]
	v_exp_f32_e32 v56, v56
	v_exp_f32_e32 v57, v57
	v_pk_fma_f32 v[52:53], v[54:55], v[164:165], v[52:53]
	v_pk_mul_f32 v[54:55], v[52:53], s[16:17] op_sel_hi:[1,0]
	v_pk_add_f32 v[56:57], v[56:57], 1.0 op_sel_hi:[1,0]
	v_exp_f32_e32 v54, v54
	v_exp_f32_e32 v55, v55
	v_rcp_f32_e32 v56, v56
	v_rcp_f32_e32 v57, v57
	v_pk_add_f32 v[54:55], v[54:55], 1.0 op_sel_hi:[1,0]
	v_rcp_f32_e32 v54, v54
	v_rcp_f32_e32 v55, v55
	v_pk_mul_f32 v[50:51], v[50:51], v[56:57]
	v_pk_mul_f32 v[56:57], v[22:23], v[50:51]
	v_mov_b32_dpp v35, v26 row_ror:1 row_mask:0xf bank_mask:0xf
	v_mov_b32_dpp v37, v26 row_ror:2 row_mask:0xf bank_mask:0xf
	v_mov_b32_dpp v39, v27 row_ror:1 row_mask:0xf bank_mask:0xf
	v_mov_b32_dpp v41, v27 row_ror:2 row_mask:0xf bank_mask:0xf
	v_mov_b32_dpp v43, v28 row_ror:1 row_mask:0xf bank_mask:0xf
	v_mov_b32_dpp v45, v28 row_ror:2 row_mask:0xf bank_mask:0xf
	v_mov_b32_dpp v50, v29 row_ror:1 row_mask:0xf bank_mask:0xf
	v_mov_b32_dpp v51, v29 row_ror:2 row_mask:0xf bank_mask:0xf
	v_pk_mul_f32 v[52:53], v[52:53], v[54:55]
	v_cndmask_b32_e64 v46, v35, v46, s[36:37]
	v_cndmask_b32_e64 v54, v47, v37, s[38:39]
	v_cndmask_b32_e64 v47, v39, v48, s[36:37]
	v_cndmask_b32_e64 v55, v49, v41, s[38:39]
	v_cndmask_b32_e64 v48, v43, v58, s[36:37]
	v_cndmask_b32_e64 v58, v59, v45, s[38:39]
	v_cndmask_b32_e64 v49, v50, v60, s[36:37]
	v_cndmask_b32_e64 v59, v61, v51, s[38:39]
	v_pk_fma_f32 v[60:61], v[26:27], v[160:161], v[162:163]
	s_nop 0
	v_pk_fma_f32 v[46:47], v[46:47], v[158:159], v[60:61]
	v_pk_fma_f32 v[60:61], v[28:29], v[152:153], v[154:155]
	v_pk_fma_f32 v[46:47], v[54:55], v[156:157], v[46:47]
	v_pk_fma_f32 v[48:49], v[48:49], v[150:151], v[60:61]
	v_pk_mul_f32 v[54:55], v[46:47], s[16:17] op_sel_hi:[1,0]
	v_pk_fma_f32 v[48:49], v[58:59], v[148:149], v[48:49]
	v_exp_f32_e32 v54, v54
	v_exp_f32_e32 v55, v55
	v_pk_mul_f32 v[58:59], v[48:49], s[16:17] op_sel_hi:[1,0]
	v_readlane_b32 s16, v253, 9
	v_exp_f32_e32 v58, v58
	v_exp_f32_e32 v59, v59
	v_pk_add_f32 v[54:55], v[54:55], 1.0 op_sel_hi:[1,0]
	v_readlane_b32 s17, v253, 10
	v_rcp_f32_e32 v54, v54
	v_rcp_f32_e32 v55, v55
	v_pk_add_f32 v[58:59], v[58:59], 1.0 op_sel_hi:[1,0]
	v_pk_mul_f32 v[60:61], v[24:25], v[52:53]
	v_rcp_f32_e32 v58, v58
	v_rcp_f32_e32 v59, v59
	v_pk_mul_f32 v[46:47], v[46:47], v[54:55]
	v_cvt_pk_bf16_f32 v52, v56, v57
	v_pk_mul_f32 v[54:55], v[18:19], v[46:47]
	v_pk_mul_f32 v[46:47], v[48:49], v[58:59]
	v_cvt_pk_bf16_f32 v54, v54, v55
	v_pk_mul_f32 v[48:49], v[20:21], v[46:47]
	v_add_u32_e32 v46, 0xa0, v183
	v_cvt_pk_bf16_f32 v55, v48, v49
	v_mov_b64_e32 v[48:49], s[16:17]
	v_mad_i64_i32 v[48:49], s[16:17], v46, s22, v[48:49]
	v_cvt_pk_bf16_f32 v53, v60, v61
	v_lshl_add_u64 v[48:49], v[146:147], 1, v[48:49]
	global_store_dwordx4 v[48:49], v[52:55], off
	s_and_saveexec_b64 s[16:17], s[40:41]
	s_cbranch_execz .LBB0_2840
	v_readlane_b32 s20, v253, 46
	v_ashrrev_i32_e32 v48, 5, v46
	v_readlane_b32 s21, v253, 47
	v_lshl_or_b32 v49, v48, 2, v138
	s_movk_i32 s5, 0x2c00
	v_mov_b64_e32 v[46:47], s[20:21]
	v_mad_i64_i32 v[46:47], s[20:21], v49, s5, v[46:47]
	v_readlane_b32 s20, v253, 48
	v_lshl_add_u64 v[46:47], v[46:47], 0, v[180:181]
	v_readlane_b32 s21, v253, 49
	global_store_dwordx4 v[46:47], v[30:33], off
	global_store_dwordx4 v[46:47], v[26:29], off offset:16
	s_nop 1
	v_lshl_or_b32 v28, v48, 1, v136
	v_mov_b64_e32 v[26:27], s[20:21]
	v_mad_i64_i32 v[26:27], s[20:21], v28, s5, v[26:27]
	v_lshl_add_u64 v[26:27], v[26:27], 0, v[180:181]
	global_store_dwordx4 v[26:27], v[22:25], off
	global_store_dwordx4 v[26:27], v[18:21], off offset:16
;     __device__ __forceinline__ void operator()(const f32x4 (&acc)[2][2][4][2], const pg8::Unit& u, int wr, int wc, int fr, int fq) const {
;     ...
;                 for (int m = 0; m < 4; ++m) {
;                     const int row = row0 + ai * 128 + m * 16;
;                     float hv[8];
; #pragma unroll
;                     for (int n = 0; n < 2; ++n) {
;                         const f32x4 g = acc[ai][0][m][n], up = acc[ai][1][m][n];
;                         f32x4 c1, c2;
; #pragma unroll
;                         for (int j = 0; j < 4; ++j) {
;                             c1[j] = __int_as_float(__builtin_amdgcn_update_dpp(0, __float_as_int(g[j]), 0x121, 0xF, 0xF, false));
;                             c2[j] = __int_as_float(__builtin_amdgcn_update_dpp(0, __float_as_int(g[j]), 0x122, 0xF, 0xF, false)); }
;                         f32x4 g1v, g2v;
; #pragma unroll
;                         for (int j = 0; j < 4; ++j) { g1v[j] = fr >= 1 ? c1[j] : p1[n][j]; g2v[j] = fr >= 2 ? c2[j] : p2[n][j]; }
; #pragma unroll
;                         for (int hh = 0; hh < 2; ++hh) {
;                             const f32x2 gg = (f32x2){g[2 * hh], g[2 * hh + 1]}, a1 = (f32x2){g1v[2 * hh], g1v[2 * hh + 1]}, a2 = (f32x2){g2v[2 * hh], g2v[2 * hh + 1]};
;                             const f32x2 t0 = (f32x2){w0[n][2 * hh], w0[n][2 * hh + 1]}, t1 = (f32x2){w1[n][2 * hh], w1[n][2 * hh + 1]}, t2 = (f32x2){w2[n][2 * hh], w2[n][2 * hh + 1]};
;                             const f32x2 y = t0 * a2 + (t1 * a1 + (t2 * gg + (f32x2){bb[n][2 * hh], bb[n][2 * hh + 1]}));
;                             const f32x2 t = y * (-1.4426950408889634f);
;                             f32x2 d = (f32x2){__builtin_amdgcn_exp2f(t.x), __builtin_amdgcn_exp2f(t.y)} + 1.0f;
;                             d = (f32x2){__builtin_amdgcn_rcpf(d.x), __builtin_amdgcn_rcpf(d.y)};
;                             const f32x2 hvv = y * d * (f32x2){up[2 * hh], up[2 * hh + 1]};
;                             hv[4 * n + 2 * hh] = hvv.x; hv[4 * n + 2 * hh + 1] = hvv.y;
;                         }
;                         p1[n] = c1; p2[n] = c2;
;                     }
;                     *(u32x4*)(o0 + (size_t)row * DFF + c0) = pack8(hv);
;                     const int rr = (m & 1) * 16 + fr;
;                     if (rr >= 30 || rr < 2) {
.LBB0_2840:
	s_or_b64 exec, exec, s[16:17]
	s_nop 0
	v_mov_b32_dpp v18, v10 row_ror:1 row_mask:0xf bank_mask:0xf
	v_mov_b32_dpp v19, v10 row_ror:2 row_mask:0xf bank_mask:0xf
	v_mov_b32_dpp v21, v11 row_ror:1 row_mask:0xf bank_mask:0xf
	v_mov_b32_dpp v22, v11 row_ror:2 row_mask:0xf bank_mask:0xf
	v_mov_b32_dpp v23, v12 row_ror:1 row_mask:0xf bank_mask:0xf
	v_mov_b32_dpp v25, v13 row_ror:1 row_mask:0xf bank_mask:0xf
	v_mov_b32_dpp v26, v13 row_ror:2 row_mask:0xf bank_mask:0xf
	v_cndmask_b32_e64 v18, v18, v34, s[36:37]
	v_cndmask_b32_e64 v20, v36, v19, s[38:39]
	v_cndmask_b32_e64 v19, v21, v38, s[36:37]
	v_cndmask_b32_e64 v21, v40, v22, s[38:39]
	v_cndmask_b32_e64 v22, v23, v42, s[36:37]
	v_cndmask_b32_e64 v23, v25, v62, s[36:37]
	v_cndmask_b32_e64 v25, v63, v26, s[38:39]
	v_pk_fma_f32 v[26:27], v[10:11], v[176:177], v[178:179]
	v_mov_b32_dpp v24, v12 row_ror:2 row_mask:0xf bank_mask:0xf
	v_pk_fma_f32 v[18:19], v[18:19], v[174:175], v[26:27]
	v_pk_fma_f32 v[26:27], v[12:13], v[168:169], v[172:173]
	v_cndmask_b32_e64 v24, v44, v24, s[38:39]
	v_pk_fma_f32 v[18:19], v[20:21], v[170:171], v[18:19]
	s_mov_b32 s16, 0xbfb8aa3b
	v_pk_fma_f32 v[22:23], v[22:23], v[166:167], v[26:27]
	v_pk_mul_f32 v[20:21], v[18:19], s[16:17] op_sel_hi:[1,0]
	v_pk_fma_f32 v[22:23], v[24:25], v[164:165], v[22:23]
	v_exp_f32_e32 v20, v20
	v_exp_f32_e32 v21, v21
	v_pk_mul_f32 v[24:25], v[22:23], s[16:17] op_sel_hi:[1,0]
	v_exp_f32_e32 v24, v24
	v_exp_f32_e32 v25, v25
	v_pk_add_f32 v[20:21], v[20:21], 1.0 op_sel_hi:[1,0]
	v_rcp_f32_e32 v20, v20
	v_rcp_f32_e32 v21, v21
	v_pk_add_f32 v[24:25], v[24:25], 1.0 op_sel_hi:[1,0]
	v_mov_b32_dpp v27, v5 row_ror:1 row_mask:0xf bank_mask:0xf
	v_rcp_f32_e32 v24, v24
	v_rcp_f32_e32 v25, v25
	v_pk_mul_f32 v[18:19], v[18:19], v[20:21]
	v_pk_mul_f32 v[14:15], v[14:15], v[18:19]
	v_pk_mul_f32 v[18:19], v[22:23], v[24:25]
	v_mov_b32_dpp v20, v2 row_ror:1 row_mask:0xf bank_mask:0xf
	v_mov_b32_dpp v21, v2 row_ror:2 row_mask:0xf bank_mask:0xf
	v_mov_b32_dpp v23, v3 row_ror:1 row_mask:0xf bank_mask:0xf
	v_mov_b32_dpp v24, v3 row_ror:2 row_mask:0xf bank_mask:0xf
	v_mov_b32_dpp v25, v4 row_ror:1 row_mask:0xf bank_mask:0xf
	v_mov_b32_dpp v28, v5 row_ror:2 row_mask:0xf bank_mask:0xf
	v_cndmask_b32_e64 v20, v20, v35, s[36:37]
	v_cndmask_b32_e64 v22, v37, v21, s[38:39]
	v_cndmask_b32_e64 v21, v23, v39, s[36:37]
	v_cndmask_b32_e64 v23, v41, v24, s[38:39]
	v_cndmask_b32_e64 v24, v25, v43, s[36:37]
	v_cndmask_b32_e64 v25, v27, v50, s[36:37]
	v_cndmask_b32_e64 v27, v51, v28, s[38:39]
	v_pk_fma_f32 v[28:29], v[2:3], v[160:161], v[162:163]
	v_mov_b32_dpp v26, v4 row_ror:2 row_mask:0xf bank_mask:0xf
	v_pk_fma_f32 v[20:21], v[20:21], v[158:159], v[28:29]
	v_pk_fma_f32 v[28:29], v[4:5], v[152:153], v[154:155]
	v_cndmask_b32_e64 v26, v45, v26, s[38:39]
	v_pk_fma_f32 v[20:21], v[22:23], v[156:157], v[20:21]
	v_pk_fma_f32 v[24:25], v[24:25], v[150:151], v[28:29]
	v_pk_mul_f32 v[22:23], v[20:21], s[16:17] op_sel_hi:[1,0]
	v_pk_fma_f32 v[24:25], v[26:27], v[148:149], v[24:25]
	v_exp_f32_e32 v22, v22
	v_exp_f32_e32 v23, v23
	v_pk_mul_f32 v[26:27], v[24:25], s[16:17] op_sel_hi:[1,0]
	v_pk_mul_f32 v[16:17], v[16:17], v[18:19]
	v_exp_f32_e32 v26, v26
	v_exp_f32_e32 v27, v27
	v_pk_add_f32 v[22:23], v[22:23], 1.0 op_sel_hi:[1,0]
	v_readlane_b32 s16, v253, 9
	v_rcp_f32_e32 v22, v22
	v_rcp_f32_e32 v23, v23
	v_pk_add_f32 v[26:27], v[26:27], 1.0 op_sel_hi:[1,0]
	v_readlane_b32 s17, v253, 10
	v_rcp_f32_e32 v26, v26
	v_rcp_f32_e32 v27, v27
	v_pk_mul_f32 v[18:19], v[20:21], v[22:23]
	v_cvt_pk_bf16_f32 v14, v14, v15
	v_pk_mul_f32 v[18:19], v[6:7], v[18:19]
	v_pk_mul_f32 v[6:7], v[24:25], v[26:27]
	v_cvt_pk_bf16_f32 v15, v16, v17
	v_pk_mul_f32 v[8:9], v[8:9], v[6:7]
	v_add_u32_e32 v6, 0xb0, v183
	v_cvt_pk_bf16_f32 v17, v8, v9
	v_mov_b64_e32 v[8:9], s[16:17]
	v_mad_i64_i32 v[8:9], s[16:17], v6, s22, v[8:9]
	v_cvt_pk_bf16_f32 v16, v18, v19
	v_lshl_add_u64 v[8:9], v[146:147], 1, v[8:9]
	global_store_dwordx4 v[8:9], v[14:17], off
	s_and_saveexec_b64 s[16:17], s[42:43]
	s_cbranch_execz .LBB0_2842
	v_ashrrev_i32_e32 v6, 5, v6
	v_readlane_b32 s20, v253, 46
	v_ashrrev_i32_e32 v7, 31, v6
	v_readlane_b32 s21, v253, 47
	v_lshl_add_u64 v[6:7], v[6:7], 2, v[140:141]
	s_movk_i32 s5, 0x2c00
	v_mov_b64_e32 v[8:9], s[20:21]
	v_mad_u64_u32 v[8:9], s[20:21], v6, s5, v[8:9]
	v_mad_i32_i24 v9, v7, s5, v9
	v_lshl_add_u64 v[6:7], v[146:147], 2, v[8:9]
	global_store_dwordx4 v[6:7], v[10:13], off
	global_store_dwordx4 v[6:7], v[2:5], off offset:16
